# v9: v8 with reversed per-phase priority (MFMA phase prio 1, softmax phase prio 0)
# baseline (speedup 1.0000x reference)
; __device__ __forceinline__ int fresh_tid(int wave) { int z = 0; asm volatile("" : "+v"(z)); return wave * 64 + (int)__builtin_amdgcn_mbcnt_hi(~0u, __builtin_amdgcn_mbcnt_lo(~0u, (unsigned)z)); }
; __device__ __forceinline__ int v_st(int k, int c) { const int kk = (k & ~0xC) | ((k & 4) << 1) | ((k & 8) >> 1); return ((kk >> 3) * 4 + (c >> 5)) * 512 + ((kk & 7) * 32 + (c & 31)) * 2; }
; __device__ __forceinline__ int v_rd_base(int lane) { return ((lane & 3) << 3) | (((lane >> 2) & 3) << 6) | (((lane >> 4) & 1) << 5) | (((lane >> 5) & 1) << 8); }
; template <int MODE>
; __device__ __forceinline__ void attn_unit(const UnitArgs& A, char* lds, const int wave_) {
;     int tid_ = fresh_tid(wave_); asm volatile("" : "+v"(tid_));
;     const int tid = tid_, wid = __builtin_amdgcn_readfirstlane(tid >> 6), lane = tid & 63, r32 = lane & 31, hi = lane >> 5;
;     const int qb = wid & 3, half = wid >> 2;
;     if (wid >= 4) __builtin_amdgcn_s_setprio(1);
;     char* V_lds = lds; char* K_lds = lds + 2 * SHM_V;
;     float* ws = (float*)(lds + OFF_WS) + wid * 64; float* li_l = ws;
;     const float* lutA = (const float*)(lds + OFF_LUTA); const float* lutB = (const float*)(lds + OFF_LUTB);
;     float l_reg = 0; f32x16 o[4] = {}; bf16x8 qr[4];
;     { const bf16_t* Qw = A.Qb + (long)(qb * QBLK + r32) * NZ + half * 64 + hi * 8;
; #pragma unroll
;       for (int d0 = 0; d0 < 4; ++d0) qr[d0] = *reinterpret_cast<const bf16x8*>(Qw + d0 * 16); }
;     const int sr = tid >> 4, sc = (tid & 15) * 8, vst0 = v_st(sr, sc);
;     const int vbase = (int)(uintptr_t)V_lds + v_rd_base(lane) + (MODE == 0 ? 0 : half * 1024);
;     const int ldk = A.ldk; const unsigned ldoff = (unsigned)(sr * ldk + sc) * 2u;
;     struct { bf16x8 vs0, vs1; } sr_[1];
;     const unsigned kdoff = (unsigned)(sr * ldk + (((tid & 15) ^ (sr & 7)) * 8)) * 2u;
;     const unsigned kdst0 = (unsigned)__builtin_amdgcn_readfirstlane((int)((unsigned)(uintptr_t)K_lds + (unsigned)wid * 1024u));
;     ...
;     auto zone_of = [&](int t) -> int { const int k0 = 64 * t, qw0 = A.q0 + 32 * qb; return (k0 + 63 - qw0 <= -128) ? 0 : ((k0 - qw0 - 31 >= 128) ? 2 : 1); };
;     ...
;     SLOAD(0, 0); asm volatile("s_waitcnt vmcnt(0)" ::: "memory"); SWRITE(0, 0); SLOAD(0, 1); __syncthreads();
;     QK(pA0, pA1, K_lds, 0); post(pA0, pA1, 0); expHalf(pA0); expHalf(pA1);
.LBB0_314:
	s_add_i32 s84, s8, s7
	s_mul_i32 s3, s84, 0x1400
	s_mul_hi_u32 s2, s84, 0x1400
	s_add_u32 s17, s37, s3
	s_addc_u32 s18, s38, s2
	s_lshl_b32 s2, s6, 7
	s_ashr_i32 s3, s2, 31
	s_lshl_b64 s[2:3], s[2:3], 1
	s_add_u32 s24, s17, s2
	s_addc_u32 s25, s18, s3
	s_mul_i32 s31, s7, 0x1400
	s_mul_hi_u32 s30, s7, 0x1400
	s_add_u32 s6, s37, s31
	s_addc_u32 s7, s38, s30
	s_add_u32 s6, s6, s2
	s_addc_u32 s7, s7, s3
	s_and_b32 s18, s1, 3
	v_and_b32_e32 v156, 31, v40
	s_lshl_b32 s28, s18, 5
	v_or_b32_e32 v0, s28, v156
	s_ashr_i32 s17, s0, 8
	v_mul_u32_u24_e32 v144, 0x1400, v0
	v_lshl_add_u64 v[0:1], s[24:25], 0, v[144:145]
	s_lshl_b32 s24, s17, 6
	v_bfe_u32 v157, v40, 5, 1
	s_ashr_i32 s25, s24, 31
	v_lshl_add_u64 v[0:1], s[24:25], 1, v[0:1]
	v_lshlrev_b32_e32 v136, 4, v157
	v_mov_b32_e32 v137, v145
	v_lshl_add_u64 v[0:1], v[0:1], 0, v[136:137]
	global_load_dwordx4 v[108:111], v[0:1], off
	global_load_dwordx4 v[104:107], v[0:1], off offset:32
	global_load_dwordx4 v[100:103], v[0:1], off offset:64
	global_load_dwordx4 v[96:99], v[0:1], off offset:96
	s_add_u32 s24, s6, 0x400
	s_addc_u32 s25, s7, 0
	s_add_u32 s26, s6, 0x800
	s_addc_u32 s27, s7, 0
	v_and_b32_e32 v137, 63, v40
	v_lshlrev_b32_e32 v176, 8, v156
	v_and_b32_e32 v178, 15, v156
	v_lshlrev_b32_e32 v178, 4, v178
	s_lshl_b32 s99, s17, 7
	v_or_b32_e32 v179, s99, v136
	v_xor_b32_e32 v179, v179, v178
	v_add_u32_e32 v176, v176, v179
	v_add_u32_e32 v164, 0x8000, v176
	v_xor_b32_e32 v165, 32, v164
	v_xor_b32_e32 v166, 64, v164
	v_xor_b32_e32 v167, 0x60, v164
	v_and_b32_e32 v176, 3, v137
	v_lshlrev_b32_e32 v176, 3, v176
	v_bfe_u32 v178, v137, 2, 2
	v_lshlrev_b32_e32 v178, 6, v178
	v_bfe_u32 v179, v137, 4, 1
	v_lshlrev_b32_e32 v179, 5, v179
	v_bfe_u32 v180, v137, 5, 1
	v_lshlrev_b32_e32 v180, 8, v180
	v_or3_b32 v176, v176, v178, v179
	v_or_b32_e32 v168, v176, v180
	v_lshrrev_b32_e32 v176, 4, v40
	v_and_b32_e32 v178, 15, v40
	v_and_b32_e32 v179, 15, v176
	v_xor_b32_e32 v178, v178, v179
	v_lshlrev_b32_e32 v178, 4, v178
	v_mul_u32_u24_e32 v176, 0x1400, v176
	v_add_u32_e32 v169, v176, v178
	v_add_u32_e32 v170, 0x28000, v169
	v_bfe_u32 v178, v137, 2, 3
	s_bfe_u32 s99, s1, 0x10001
	s_lshl_b32 s99, s99, 3
	s_bfe_u32 s6, s1, 0x10002
	s_lshl_b32 s6, s6, 4
	s_or_b32 s99, s99, s6
	v_or_b32_e32 v178, s99, v178
	v_mul_u32_u24_e32 v178, 0x1400, v178
	s_and_b32 s99, s1, 1
	s_lshl_b32 s99, s99, 7
	v_bfe_u32 v176, v137, 5, 1
	v_lshlrev_b32_e32 v176, 6, v176
	v_and_b32_e32 v179, 3, v137
	v_lshlrev_b32_e32 v179, 4, v179
	v_add3_u32 v178, v178, v176, v179
	v_add_u32_e32 v171, s99, v178
	v_add_u32_e32 v172, 0x28000, v171
	s_lshl_b32 s33, s1, 10
	s_add_u32 s31, s33, 0x8000
	s_add_i32 s99, s8, s28
	s_sub_i32 s29, s99, 0xbf
	s_add_i32 s30, s99, 0x9f
	s_sub_i32 s35, 0x140, s99
	s_lshl_b32 s35, s35, 2
	s_add_i32 s35, s35, s19
	v_lshlrev_b32_e32 v176, 2, v157
	v_sub_u32_e32 v176, v176, v156
	v_lshlrev_b32_e32 v174, 2, v176
	v_mov_b32_e32 v176, s13
	v_sub_f32_e32 v178, s21, v176
	v_sub_f32_e32 v179, s20, v176
	s_xor_b32 s98, s13, 0x80000000
	s_sub_i32 s20, s22, 1
	v_readfirstlane_b32 s21, v178
	v_readfirstlane_b32 s22, v179
	s_mov_b32 s34, 0
	s_mov_b32 s23, 0
	s_cmp_le_i32 s23, s29
	s_cselect_b32 s9, s21, s98
	v_mov_b32_e32 v68, s9
	v_mov_b32_e32 v69, s9
	v_mov_b32_e32 v70, s9
	v_mov_b32_e32 v71, s9
	v_mov_b32_e32 v72, s9
	v_mov_b32_e32 v73, s9
	v_mov_b32_e32 v74, s9
	v_mov_b32_e32 v75, s9
	v_mov_b32_e32 v76, s9
	v_mov_b32_e32 v77, s9
	v_mov_b32_e32 v78, s9
	v_mov_b32_e32 v79, s9
	v_mov_b32_e32 v80, s9
	v_mov_b32_e32 v81, s9
	v_mov_b32_e32 v82, s9
	v_mov_b32_e32 v83, s9
	v_mov_b32_e32 v0, 0
	v_mov_b32_e32 v1, 0
	v_mov_b32_e32 v2, 0
	v_mov_b32_e32 v3, 0
	v_mov_b32_e32 v4, 0
	v_mov_b32_e32 v5, 0
	v_mov_b32_e32 v6, 0
	v_mov_b32_e32 v7, 0
	v_mov_b32_e32 v8, 0
	v_mov_b32_e32 v9, 0
	v_mov_b32_e32 v10, 0
	v_mov_b32_e32 v11, 0
	v_mov_b32_e32 v12, 0
	v_mov_b32_e32 v13, 0
	v_mov_b32_e32 v14, 0
	v_mov_b32_e32 v15, 0
	v_mov_b32_e32 v16, 0
	v_mov_b32_e32 v17, 0
	v_mov_b32_e32 v18, 0
	v_mov_b32_e32 v19, 0
	v_mov_b32_e32 v20, 0
	v_mov_b32_e32 v21, 0
	v_mov_b32_e32 v22, 0
	v_mov_b32_e32 v23, 0
	v_mov_b32_e32 v24, 0
	v_mov_b32_e32 v25, 0
	v_mov_b32_e32 v26, 0
	v_mov_b32_e32 v27, 0
	v_mov_b32_e32 v28, 0
	v_mov_b32_e32 v29, 0
	v_mov_b32_e32 v30, 0
	v_mov_b32_e32 v31, 0
	v_mov_b32_e32 v32, 0
	v_mov_b32_e32 v33, 0
	v_mov_b32_e32 v34, 0
	v_mov_b32_e32 v35, 0
	v_mov_b32_e32 v36, 0
	v_mov_b32_e32 v37, 0
	v_mov_b32_e32 v38, 0
	v_mov_b32_e32 v39, 0
	v_mov_b32_e32 v40, 0
	v_mov_b32_e32 v41, 0
	v_mov_b32_e32 v42, 0
	v_mov_b32_e32 v43, 0
	v_mov_b32_e32 v44, 0
	v_mov_b32_e32 v45, 0
	v_mov_b32_e32 v46, 0
	v_mov_b32_e32 v47, 0
	v_mov_b32_e32 v48, 0
	v_mov_b32_e32 v49, 0
	v_mov_b32_e32 v50, 0
	v_mov_b32_e32 v51, 0
	v_mov_b32_e32 v52, 0
	v_mov_b32_e32 v53, 0
	v_mov_b32_e32 v54, 0
	v_mov_b32_e32 v55, 0
	v_mov_b32_e32 v56, 0
	v_mov_b32_e32 v57, 0
	v_mov_b32_e32 v58, 0
	v_mov_b32_e32 v59, 0
	v_mov_b32_e32 v60, 0
	v_mov_b32_e32 v61, 0
	v_mov_b32_e32 v62, 0
	v_mov_b32_e32 v63, 0
	v_mov_b32_e32 v64, 0
	v_mov_b32_e32 v65, 0
	v_mov_b32_e32 v66, 0
	v_mov_b32_e32 v67, 0
	v_mov_b32_e32 v178, 0
	v_mov_b32_e32 v179, 0
	v_mov_b32_e32 v180, 0
	v_mov_b32_e32 v181, 0
	s_mov_b32 s100, 0x4000
	s_mov_b32 s101, 0x10200
	s_mov_b32 s32, 0xfffebe00
	s_mov_b32 m0, s31
	s_add_u32 s7, s31, 0x2000
	global_load_lds_dwordx4 v169, s[24:25]
	s_mov_b32 m0, s7
	s_add_u32 s31, s31, s100
	global_load_lds_dwordx4 v170, s[24:25]
	s_add_u32 s24, s24, 0x50000
	s_addc_u32 s25, s25, 0
	s_mov_b32 m0, s31
	s_add_u32 s7, s31, 0x2000
	global_load_lds_dwordx4 v169, s[24:25]
	s_mov_b32 m0, s7
	s_add_u32 s31, s31, s101
	global_load_lds_dwordx4 v170, s[24:25]
	s_add_u32 s24, s24, 0x50000
	s_addc_u32 s25, s25, 0
	s_mov_b32 m0, s31
	s_add_u32 s7, s31, 0x2000
	global_load_lds_dwordx4 v169, s[24:25]
	s_mov_b32 m0, s7
	s_add_u32 s31, s31, s32
	global_load_lds_dwordx4 v170, s[24:25]
	s_add_u32 s24, s24, 0x50000
	s_addc_u32 s25, s25, 0
	s_mov_b32 m0, s33
	s_add_u32 s7, s33, 0x2000
	global_load_lds_dwordx4 v171, s[26:27]
	s_mov_b32 m0, s7
	s_xor_b32 s33, s33, 0x4000
	global_load_lds_dwordx4 v172, s[26:27]
	s_add_u32 s26, s26, 0x50000
	s_addc_u32 s27, s27, 0
	s_waitcnt vmcnt(0)
	s_barrier
; #define SBAR() __builtin_amdgcn_sched_barrier(0)
; #define KFRAG(d0, row) (*reinterpret_cast<const bf16x8*>(Ks + KSWZ((row), (half * 64 + (d0) * 16 + hi * 8) * 2)))
; __device__ __forceinline__ void qkt(f32x16& p0, f32x16& p1, const char* Ks, const bf16x8* qr, float c0, int r32, int hi, int half) {
;     ...
;     bf16x8 a0 = KFRAG(0, r32), a1 = KFRAG(0, 32 + r32), b0 = KFRAG(1, r32), b1 = KFRAG(1, 32 + r32);
;     SBAR();
; #pragma unroll
;     for (int r = 0; r < 16; ++r) { p0[r] = c0; p1[r] = c0; }
;     SBAR();
;     p0 = __builtin_amdgcn_mfma_f32_32x32x16_bf16(a0, qr[0], p0, 0, 0, 0); p1 = __builtin_amdgcn_mfma_f32_32x32x16_bf16(a1, qr[0], p1, 0, 0, 0);
;     a0 = KFRAG(2, r32); a1 = KFRAG(2, 32 + r32);
;     SBAR();
;     p0 = __builtin_amdgcn_mfma_f32_32x32x16_bf16(b0, qr[1], p0, 0, 0, 0); p1 = __builtin_amdgcn_mfma_f32_32x32x16_bf16(b1, qr[1], p1, 0, 0, 0);
;     b0 = KFRAG(3, r32); b1 = KFRAG(3, 32 + r32);
;     SBAR();
;     p0 = __builtin_amdgcn_mfma_f32_32x32x16_bf16(a0, qr[2], p0, 0, 0, 0); p1 = __builtin_amdgcn_mfma_f32_32x32x16_bf16(a1, qr[2], p1, 0, 0, 0);
;     p0 = __builtin_amdgcn_mfma_f32_32x32x16_bf16(b0, qr[3], p0, 0, 0, 0); p1 = __builtin_amdgcn_mfma_f32_32x32x16_bf16(b1, qr[3], p1, 0, 0, 0);
;     ...
; }
; template <int MODE>
; __device__ __forceinline__ void attn_unit(const UnitArgs& A, char* lds, const int wave_) {
;     ...
;     auto post = [&](f32x16& p0, f32x16& p1, int t) {
;         SBAR();
;         if (MODE == 0) {
;             if (zone_of(t) == 1) { const int k0 = 64 * t, qw0 = A.q0 + 32 * qb;
;                 const float* b = lutA + A.h * LUTA_STRIDE + (k0 - qw0 - r32 + 4 * hi + 320);
; #pragma unroll
;                 for (int r = 0; r < 16; ++r) { const int c = (r & 3) + 8 * (r >> 2); p0[r] += b[c]; p1[r] += b[32 + c]; } }
	s_cmp_lg_u32 s17, 0
	s_cbranch_scc1 .Lat_g1
	s_setprio 1
	ds_read_b128 v[224:227], v164
	ds_read_b128 v[228:231], v164 offset:8192
	ds_read_b128 v[232:235], v165
	ds_read_b128 v[236:239], v165 offset:8192
	ds_read_b128 v[240:243], v166
	ds_read_b128 v[244:247], v166 offset:8192
	ds_read_b128 v[248:251], v167
	ds_read_b128 v[188:191], v167 offset:8192
	v_add_u32_e32 v164, s100, v164
	v_add_u32_e32 v165, s100, v165
	v_add_u32_e32 v166, s100, v166
	v_add_u32_e32 v167, s100, v167
	s_waitcnt lgkmcnt(7)
	v_mfma_f32_32x32x16_bf16 v[112:127], v[224:227], v[108:111], v[68:83]
	s_waitcnt lgkmcnt(6)
	v_mfma_f32_32x32x16_bf16 v[192:207], v[228:231], v[108:111], v[68:83]
	s_waitcnt lgkmcnt(5)
	v_mfma_f32_32x32x16_bf16 v[112:127], v[232:235], v[104:107], v[112:127]
	s_waitcnt lgkmcnt(4)
	v_mfma_f32_32x32x16_bf16 v[192:207], v[236:239], v[104:107], v[192:207]
	s_waitcnt lgkmcnt(3)
	v_mfma_f32_32x32x16_bf16 v[112:127], v[240:243], v[100:103], v[112:127]
	s_waitcnt lgkmcnt(2)
	v_mfma_f32_32x32x16_bf16 v[192:207], v[244:247], v[100:103], v[192:207]
	s_waitcnt lgkmcnt(1)
	v_mfma_f32_32x32x16_bf16 v[112:127], v[248:251], v[96:99], v[112:127]
	s_waitcnt lgkmcnt(0)
	v_mfma_f32_32x32x16_bf16 v[192:207], v[188:191], v[96:99], v[192:207]
	s_nop 7
	s_nop 3
	s_barrier
.Lat_g0_loop:
	s_setprio 0
	s_cmp_gt_i32 s23, s29
	s_cselect_b32 s99, 1, 0
	s_cmp_lt_i32 s23, s30
	s_cselect_b32 s6, 1, 0
	s_and_b32 s99, s99, s6
	s_cbranch_scc0 .Lat_far_g0l
	v_add_u32_e32 v186, s35, v174
	ds_read2_b32 v[224:225], v186 offset0:0 offset1:1
	ds_read2_b32 v[226:227], v186 offset0:2 offset1:3
	ds_read2_b32 v[228:229], v186 offset0:8 offset1:9
	ds_read2_b32 v[230:231], v186 offset0:10 offset1:11
	ds_read2_b32 v[232:233], v186 offset0:16 offset1:17
	ds_read2_b32 v[234:235], v186 offset0:18 offset1:19
	ds_read2_b32 v[236:237], v186 offset0:24 offset1:25
	ds_read2_b32 v[238:239], v186 offset0:26 offset1:27
	s_waitcnt lgkmcnt(4)
	ds_read2_b32 v[240:241], v186 offset0:32 offset1:33
	ds_read2_b32 v[242:243], v186 offset0:34 offset1:35
	ds_read2_b32 v[244:245], v186 offset0:40 offset1:41
	ds_read2_b32 v[246:247], v186 offset0:42 offset1:43
	ds_read2_b32 v[248:249], v186 offset0:48 offset1:49
	ds_read2_b32 v[250:251], v186 offset0:50 offset1:51
	ds_read2_b32 v[188:189], v186 offset0:56 offset1:57
	ds_read2_b32 v[190:191], v186 offset0:58 offset1:59
	s_waitcnt lgkmcnt(8)
	v_add_f32_e32 v112, v112, v224
	v_add_f32_e32 v113, v113, v225
	v_add_f32_e32 v114, v114, v226
	v_add_f32_e32 v115, v115, v227
	v_add_f32_e32 v116, v116, v228
	v_add_f32_e32 v117, v117, v229
	v_add_f32_e32 v118, v118, v230
	v_add_f32_e32 v119, v119, v231
	v_add_f32_e32 v120, v120, v232
	v_add_f32_e32 v121, v121, v233
	v_add_f32_e32 v122, v122, v234
	v_add_f32_e32 v123, v123, v235
	v_add_f32_e32 v124, v124, v236
	v_add_f32_e32 v125, v125, v237
	v_add_f32_e32 v126, v126, v238
	v_add_f32_e32 v127, v127, v239
	s_waitcnt lgkmcnt(0)
	v_add_f32_e32 v192, v192, v240
	v_add_f32_e32 v193, v193, v241
	v_add_f32_e32 v194, v194, v242
	v_add_f32_e32 v195, v195, v243
	v_add_f32_e32 v196, v196, v244
	v_add_f32_e32 v197, v197, v245
	v_add_f32_e32 v198, v198, v246
	v_add_f32_e32 v199, v199, v247
	v_add_f32_e32 v200, v200, v248
	v_add_f32_e32 v201, v201, v249
	v_add_f32_e32 v202, v202, v250
	v_add_f32_e32 v203, v203, v251
	v_add_f32_e32 v204, v204, v188
	v_add_f32_e32 v205, v205, v189
	v_add_f32_e32 v206, v206, v190
	v_add_f32_e32 v207, v207, v191

; #define SBAR() __builtin_amdgcn_sched_barrier(0)
; __device__ __forceinline__ void qkt(f32x16& p0, f32x16& p1, const char* Ks, const bf16x8* qr, float c0, int r32, int hi, int half) {
;     ...
;     bf16x8 a0 = KFRAG(0, r32), a1 = KFRAG(0, 32 + r32), b0 = KFRAG(1, r32), b1 = KFRAG(1, 32 + r32);
;     SBAR();
; #pragma unroll
;     for (int r = 0; r < 16; ++r) { p0[r] = c0; p1[r] = c0; }
;     SBAR();
;     p0 = __builtin_amdgcn_mfma_f32_32x32x16_bf16(a0, qr[0], p0, 0, 0, 0); p1 = __builtin_amdgcn_mfma_f32_32x32x16_bf16(a1, qr[0], p1, 0, 0, 0);
;     a0 = KFRAG(2, r32); a1 = KFRAG(2, 32 + r32);
;     SBAR();
;     p0 = __builtin_amdgcn_mfma_f32_32x32x16_bf16(b0, qr[1], p0, 0, 0, 0); p1 = __builtin_amdgcn_mfma_f32_32x32x16_bf16(b1, qr[1], p1, 0, 0, 0);
;     b0 = KFRAG(3, r32); b1 = KFRAG(3, 32 + r32);
;     SBAR();
;     p0 = __builtin_amdgcn_mfma_f32_32x32x16_bf16(a0, qr[2], p0, 0, 0, 0); p1 = __builtin_amdgcn_mfma_f32_32x32x16_bf16(a1, qr[2], p1, 0, 0, 0);
;     p0 = __builtin_amdgcn_mfma_f32_32x32x16_bf16(b0, qr[3], p0, 0, 0, 0); p1 = __builtin_amdgcn_mfma_f32_32x32x16_bf16(b1, qr[3], p1, 0, 0, 0);
;     ...
; }
; __device__ __forceinline__ int v_st(int k, int c) { const int kk = (k & ~0xC) | ((k & 4) << 1) | ((k & 8) >> 1); return ((kk >> 3) * 4 + (c >> 5)) * 512 + ((kk & 7) * 32 + (c & 31)) * 2; }
; __device__ __forceinline__ int v_rd_base(int lane) { return ((lane & 3) << 3) | (((lane >> 2) & 3) << 6) | (((lane >> 4) & 1) << 5) | (((lane >> 5) & 1) << 8); }
; template <int OFF> __device__ __forceinline__ s16x4 tr_read(int vb) { s16x4 r; asm volatile("ds_read_b64_tr_b16 %0, %1 offset:%2" : "=&v"(r) : "v"(vb), "i"(OFF) : "memory"); return r; }
; template <int MODE>
; __device__ __forceinline__ void attn_unit(const UnitArgs& A, char* lds, const int wave_) {
;     ...
;     for (int j = 1; j + 1 < NT; j += 2) {
;         SBAR(); QK(pB0, pB1, K_lds + SHM_K, j);
;         finishSM(pA0, pA1, l_reg, pa0, pa1, pa2, pa3); SBAR();
;         SLOAD(0, j + 1); SBAR();
;         post(pB0, pB1, j); PV(0, pB0, pB1);
;         __syncthreads(); SWAIT(); SWRITE(0, 0);
;         __syncthreads();
;         SBAR(); QK(pA0, pA1, K_lds, j + 1);
;         finishSM(pB0, pB1, l_reg, pa0, pa1, pa2, pa3); SBAR();
;         SLOAD(0, j + 2); SBAR();
;         post(pA0, pA1, j + 1); PV(1, pA0, pA1);
;         __syncthreads(); SWAIT(); SWRITE(1, 0);
;         __syncthreads();
.Lat_c0same_g0l:
	ds_read_b128 v[224:227], v164
	ds_read_b128 v[228:231], v164 offset:8192
	ds_read_b128 v[232:235], v165
	ds_read_b128 v[236:239], v165 offset:8192
	ds_read_b128 v[240:243], v166
	ds_read_b128 v[244:247], v166 offset:8192
	ds_read_b128 v[248:251], v167
	ds_read_b128 v[188:191], v167 offset:8192
	v_add_u32_e32 v164, s101, v164
	v_add_u32_e32 v165, s101, v165
	v_add_u32_e32 v166, s101, v166
	v_add_u32_e32 v167, s101, v167
	s_waitcnt vmcnt(2)
	s_barrier
	s_setprio 1
	s_waitcnt lgkmcnt(7)
	v_mfma_f32_32x32x16_bf16 v[112:127], v[224:227], v[108:111], v[68:83]
	s_waitcnt lgkmcnt(6)
	v_mfma_f32_32x32x16_bf16 v[192:207], v[228:231], v[108:111], v[68:83]
	ds_read_b64_tr_b16 v[84:85], v168 offset:0
	ds_read_b64_tr_b16 v[86:87], v168 offset:2048
	s_waitcnt lgkmcnt(7)
	v_mfma_f32_32x32x16_bf16 v[112:127], v[232:235], v[104:107], v[112:127]
	ds_read_b64_tr_b16 v[88:89], v168 offset:4096
	ds_read_b64_tr_b16 v[90:91], v168 offset:6144
	s_waitcnt lgkmcnt(8)
	v_mfma_f32_32x32x16_bf16 v[192:207], v[236:239], v[104:107], v[192:207]
	ds_read_b64_tr_b16 v[92:93], v168 offset:8192
	ds_read_b64_tr_b16 v[94:95], v168 offset:10240
	s_waitcnt lgkmcnt(9)
	v_mfma_f32_32x32x16_bf16 v[112:127], v[240:243], v[100:103], v[112:127]
	ds_read_b64_tr_b16 v[128:129], v168 offset:12288
	ds_read_b64_tr_b16 v[130:131], v168 offset:14336
	s_waitcnt lgkmcnt(10)
	v_mfma_f32_32x32x16_bf16 v[192:207], v[244:247], v[100:103], v[192:207]
	ds_read_b64_tr_b16 v[132:133], v168 offset:512
	ds_read_b64_tr_b16 v[134:135], v168 offset:2560
	s_waitcnt lgkmcnt(11)
	v_mfma_f32_32x32x16_bf16 v[112:127], v[248:251], v[96:99], v[112:127]
	ds_read_b64_tr_b16 v[140:141], v168 offset:4608
	ds_read_b64_tr_b16 v[142:143], v168 offset:6656
	s_waitcnt lgkmcnt(12)
	v_mfma_f32_32x32x16_bf16 v[192:207], v[188:191], v[96:99], v[192:207]
	ds_read_b64_tr_b16 v[152:153], v168 offset:8704
	ds_read_b64_tr_b16 v[154:155], v168 offset:10752
	s_waitcnt lgkmcnt(12)
	v_mfma_f32_32x32x16_bf16 v[0:15], v[208:211], v[84:87], v[0:15]
	ds_read_b64_tr_b16 v[160:161], v168 offset:12800
	ds_read_b64_tr_b16 v[162:163], v168 offset:14848
	s_waitcnt lgkmcnt(12)
	v_mfma_f32_32x32x16_bf16 v[0:15], v[212:215], v[88:91], v[0:15]
	ds_read_b64_tr_b16 v[84:85], v168 offset:1024
	ds_read_b64_tr_b16 v[86:87], v168 offset:3072
	s_waitcnt lgkmcnt(12)
	v_mfma_f32_32x32x16_bf16 v[0:15], v[216:219], v[92:95], v[0:15]
	ds_read_b64_tr_b16 v[88:89], v168 offset:5120
	ds_read_b64_tr_b16 v[90:91], v168 offset:7168
	s_waitcnt lgkmcnt(12)
	v_mfma_f32_32x32x16_bf16 v[0:15], v[220:223], v[128:131], v[0:15]
	ds_read_b64_tr_b16 v[92:93], v168 offset:9216
	ds_read_b64_tr_b16 v[94:95], v168 offset:11264
	s_waitcnt lgkmcnt(12)
	v_mfma_f32_32x32x16_bf16 v[16:31], v[208:211], v[132:135], v[16:31]
	ds_read_b64_tr_b16 v[128:129], v168 offset:13312
	ds_read_b64_tr_b16 v[130:131], v168 offset:15360
	s_mov_b32 m0, s33
	s_add_u32 s7, s33, 0x2000
	global_load_lds_dwordx4 v171, s[26:27]
	s_waitcnt lgkmcnt(12)
	v_mfma_f32_32x32x16_bf16 v[16:31], v[212:215], v[140:143], v[16:31]
	ds_read_b64_tr_b16 v[132:133], v168 offset:1536
	ds_read_b64_tr_b16 v[134:135], v168 offset:3584
	s_waitcnt lgkmcnt(12)
	v_mfma_f32_32x32x16_bf16 v[16:31], v[216:219], v[152:155], v[16:31]
	ds_read_b64_tr_b16 v[140:141], v168 offset:5632
	ds_read_b64_tr_b16 v[142:143], v168 offset:7680
	s_waitcnt lgkmcnt(12)
	v_mfma_f32_32x32x16_bf16 v[16:31], v[220:223], v[160:163], v[16:31]
	ds_read_b64_tr_b16 v[152:153], v168 offset:9728
	ds_read_b64_tr_b16 v[154:155], v168 offset:11776
	s_mov_b32 m0, s7
	s_xor_b32 s33, s33, 0x4000
	global_load_lds_dwordx4 v172, s[26:27]
	s_add_u32 s26, s26, 0x50000
	s_addc_u32 s27, s27, 0
	s_waitcnt lgkmcnt(12)
	v_mfma_f32_32x32x16_bf16 v[32:47], v[208:211], v[84:87], v[32:47]
	ds_read_b64_tr_b16 v[160:161], v168 offset:13824
	ds_read_b64_tr_b16 v[162:163], v168 offset:15872
	v_xor_b32_e32 v168, 0x4000, v168
	s_waitcnt lgkmcnt(12)
	v_mfma_f32_32x32x16_bf16 v[32:47], v[212:215], v[88:91], v[32:47]
	s_waitcnt lgkmcnt(10)
	v_mfma_f32_32x32x16_bf16 v[32:47], v[216:219], v[92:95], v[32:47]
	s_mov_b32 m0, s31
	s_add_u32 s7, s31, 0x2000
	global_load_lds_dwordx4 v169, s[24:25]
	s_waitcnt lgkmcnt(8)
	v_mfma_f32_32x32x16_bf16 v[32:47], v[220:223], v[128:131], v[32:47]
	s_waitcnt lgkmcnt(6)
	v_mfma_f32_32x32x16_bf16 v[48:63], v[208:211], v[132:135], v[48:63]
	s_waitcnt lgkmcnt(4)
	v_mfma_f32_32x32x16_bf16 v[48:63], v[212:215], v[140:143], v[48:63]
	s_mov_b32 m0, s7
	s_add_u32 s31, s31, s100
	global_load_lds_dwordx4 v170, s[24:25]
	s_add_u32 s24, s24, 0x50000
	s_addc_u32 s25, s25, 0
	s_waitcnt lgkmcnt(2)
	v_mfma_f32_32x32x16_bf16 v[48:63], v[216:219], v[152:155], v[48:63]
	s_waitcnt lgkmcnt(0)
	v_mfma_f32_32x32x16_bf16 v[48:63], v[220:223], v[160:163], v[48:63]
	s_add_i32 s34, s34, 1
	s_add_i32 s23, s23, 64
	s_addk_i32 s35, 0x100
	s_mov_b32 s8, s100
	s_mov_b32 s100, s101
	s_mov_b32 s101, s32
	s_mov_b32 s32, s8
	s_waitcnt vmcnt(4)
	s_barrier
	s_cmp_lt_u32 s34, s20
	s_cbranch_scc1 .Lat_g0_loop
	s_setprio 0
	s_cmp_gt_i32 s23, s29
	s_cselect_b32 s99, 1, 0
	s_cmp_lt_i32 s23, s30
	s_cselect_b32 s6, 1, 0
	s_and_b32 s99, s99, s6
	s_cbranch_scc0 .Lat_far_g0p
; #define SBAR() __builtin_amdgcn_sched_barrier(0)
; template <int MODE>
; __device__ __forceinline__ void attn_unit(const UnitArgs& A, char* lds, const int wave_) {
;     ...
;     auto post = [&](f32x16& p0, f32x16& p1, int t) {
;         SBAR();
;         if (MODE == 0) {
;             if (zone_of(t) == 1) { const int k0 = 64 * t, qw0 = A.q0 + 32 * qb;
;                 const float* b = lutA + A.h * LUTA_STRIDE + (k0 - qw0 - r32 + 4 * hi + 320);
; #pragma unroll
;                 for (int r = 0; r < 16; ++r) { const int c = (r & 3) + 8 * (r >> 2); p0[r] += b[c]; p1[r] += b[32 + c]; } }
	v_add_u32_e32 v186, s35, v174
	ds_read2_b32 v[224:225], v186 offset0:0 offset1:1
	ds_read2_b32 v[226:227], v186 offset0:2 offset1:3
	ds_read2_b32 v[228:229], v186 offset0:8 offset1:9
	ds_read2_b32 v[230:231], v186 offset0:10 offset1:11
	ds_read2_b32 v[232:233], v186 offset0:16 offset1:17
	ds_read2_b32 v[234:235], v186 offset0:18 offset1:19
	ds_read2_b32 v[236:237], v186 offset0:24 offset1:25
	ds_read2_b32 v[238:239], v186 offset0:26 offset1:27
	s_waitcnt lgkmcnt(4)
	ds_read2_b32 v[240:241], v186 offset0:32 offset1:33
	ds_read2_b32 v[242:243], v186 offset0:34 offset1:35
	ds_read2_b32 v[244:245], v186 offset0:40 offset1:41
	ds_read2_b32 v[246:247], v186 offset0:42 offset1:43
	ds_read2_b32 v[248:249], v186 offset0:48 offset1:49
	ds_read2_b32 v[250:251], v186 offset0:50 offset1:51
	ds_read2_b32 v[188:189], v186 offset0:56 offset1:57
	ds_read2_b32 v[190:191], v186 offset0:58 offset1:59
	s_waitcnt lgkmcnt(8)
	v_add_f32_e32 v112, v112, v224
	v_add_f32_e32 v113, v113, v225
	v_add_f32_e32 v114, v114, v226
	v_add_f32_e32 v115, v115, v227
	v_add_f32_e32 v116, v116, v228
	v_add_f32_e32 v117, v117, v229
	v_add_f32_e32 v118, v118, v230
	v_add_f32_e32 v119, v119, v231
	v_add_f32_e32 v120, v120, v232
	v_add_f32_e32 v121, v121, v233
	v_add_f32_e32 v122, v122, v234
	v_add_f32_e32 v123, v123, v235
	v_add_f32_e32 v124, v124, v236
	v_add_f32_e32 v125, v125, v237
	v_add_f32_e32 v126, v126, v238
	v_add_f32_e32 v127, v127, v239
	s_waitcnt lgkmcnt(0)
	v_add_f32_e32 v192, v192, v240
	v_add_f32_e32 v193, v193, v241
	v_add_f32_e32 v194, v194, v242
	v_add_f32_e32 v195, v195, v243
	v_add_f32_e32 v196, v196, v244
	v_add_f32_e32 v197, v197, v245
	v_add_f32_e32 v198, v198, v246
	v_add_f32_e32 v199, v199, v247
	v_add_f32_e32 v200, v200, v248
	v_add_f32_e32 v201, v201, v249
	v_add_f32_e32 v202, v202, v250
	v_add_f32_e32 v203, v203, v251
	v_add_f32_e32 v204, v204, v188
	v_add_f32_e32 v205, v205, v189
	v_add_f32_e32 v206, v206, v190
	v_add_f32_e32 v207, v207, v191
; #define SBAR() __builtin_amdgcn_sched_barrier(0)
; #define PVLOAD(D0, X) do { X[0] = tr_read<v_rd_off(D0, 0, 0)>(vb); X[1] = tr_read<v_rd_off(D0, 0, 1)>(vb); X[2] = tr_read<v_rd_off(D0, 1, 0)>(vb); X[3] = tr_read<v_rd_off(D0, 1, 1)>(vb); \
;     X[4] = tr_read<v_rd_off(D0, 2, 0)>(vb); X[5] = tr_read<v_rd_off(D0, 2, 1)>(vb); X[6] = tr_read<v_rd_off(D0, 3, 0)>(vb); X[7] = tr_read<v_rd_off(D0, 3, 1)>(vb); } while (0)
; #define PVMMA(OD, X) do { OD = __builtin_amdgcn_mfma_f32_32x32x16_bf16(pa0, PVPK(X[0], X[1]), OD, 0, 0, 0); OD = __builtin_amdgcn_mfma_f32_32x32x16_bf16(pa1, PVPK(X[2], X[3]), OD, 0, 0, 0); \
;     OD = __builtin_amdgcn_mfma_f32_32x32x16_bf16(pa2, PVPK(X[4], X[5]), OD, 0, 0, 0); OD = __builtin_amdgcn_mfma_f32_32x32x16_bf16(pa3, PVPK(X[6], X[7]), OD, 0, 0, 0); } while (0)
; #define PVWAIT() do { asm volatile("s_waitcnt lgkmcnt(0)" ::: "memory"); SBAR(); } while (0)
; #define PVEXP(P, B, N) do { _Pragma("unroll") for (int r = (B); r < (B) + (N); ++r) P[r] = __builtin_amdgcn_exp2f(P[r]); } while (0)
; __device__ __forceinline__ void expHalf(f32x16& p0) {
; #pragma unroll
;     for (int r = 0; r < 16; ++r) p0[r] = __builtin_amdgcn_exp2f(p0[r]);
; }
; __device__ __forceinline__ void finishSM(f32x16& p0, f32x16& p1, float& l_reg, bf16x8& pa0, bf16x8& pa1, bf16x8& pa2, bf16x8& pa3) {
;     float ps = 0;
; #pragma unroll
;     for (int r = 0; r < 16; ++r) ps += p0[r];
; #pragma unroll
;     for (int r = 0; r < 16; ++r) ps += p1[r];
;     l_reg += ps;
;     ...
;     PK4(p0, 0, pa0); PK4(p0, 8, pa1); PK4(p1, 0, pa2); PK4(p1, 8, pa3);
;     ...
; }
; template <int NB> __device__ __forceinline__ void pv_blocks(f32x16* o, int vb, bf16x8 pa0, bf16x8 pa1, bf16x8 pa2, bf16x8 pa3, f32x16& pe0, f32x16& pe1) {
;     s16x4 x[8], y[8];
;     ...
;     PVLOAD(0, x); PVWAIT();
;     if (NB == 4) {
;         PVLOAD(1, y); SBAR(); PVMMA(o[0], x); PVEXP(pe0, 0, 8); SBAR(); PVWAIT();
;         PVLOAD(2, x); SBAR(); PVMMA(o[1], y); PVEXP(pe0, 8, 8); SBAR(); PVWAIT();
;         PVLOAD(3, y); SBAR(); PVMMA(o[2], x); PVEXP(pe1, 0, 8); SBAR(); PVWAIT();
;         PVMMA(o[3], y); PVEXP(pe1, 8, 8);
;     } else {
;         PVLOAD(1, y); SBAR(); PVMMA(o[0], x); PVEXP(pe0, 0, 16); SBAR(); PVWAIT();
;         PVMMA(o[1], y); PVEXP(pe1, 0, 16);
;     }
;     ...
; }
.Lat_far_g0p:
	v_exp_f32_e32 v112, v112
	v_exp_f32_e32 v113, v113
	v_exp_f32_e32 v114, v114
	v_exp_f32_e32 v115, v115
	v_exp_f32_e32 v116, v116
	v_exp_f32_e32 v117, v117
	v_exp_f32_e32 v118, v118
	v_exp_f32_e32 v119, v119
	v_exp_f32_e32 v120, v120
	v_exp_f32_e32 v121, v121
	v_exp_f32_e32 v122, v122
	v_exp_f32_e32 v123, v123
	v_exp_f32_e32 v124, v124
	v_exp_f32_e32 v125, v125
	v_exp_f32_e32 v126, v126
	v_exp_f32_e32 v127, v127
	v_exp_f32_e32 v192, v192
	v_add_f32_e32 v64, v64, v112
	v_exp_f32_e32 v193, v193
	v_add_f32_e32 v65, v65, v113
	v_exp_f32_e32 v194, v194
	v_add_f32_e32 v66, v66, v114
	v_exp_f32_e32 v195, v195
	v_add_f32_e32 v67, v67, v115
	v_exp_f32_e32 v196, v196
	v_add_f32_e32 v64, v64, v116
	v_exp_f32_e32 v197, v197
	v_add_f32_e32 v65, v65, v117
	v_exp_f32_e32 v198, v198
	v_add_f32_e32 v66, v66, v118
	v_exp_f32_e32 v199, v199
	v_add_f32_e32 v67, v67, v119
	v_exp_f32_e32 v200, v200
	v_add_f32_e32 v64, v64, v120
	v_exp_f32_e32 v201, v201
	v_add_f32_e32 v65, v65, v121
	v_exp_f32_e32 v202, v202
	v_add_f32_e32 v66, v66, v122
	v_exp_f32_e32 v203, v203
	v_add_f32_e32 v67, v67, v123
	v_exp_f32_e32 v204, v204
	v_add_f32_e32 v64, v64, v124
	v_exp_f32_e32 v205, v205
	v_add_f32_e32 v65, v65, v125
	v_exp_f32_e32 v206, v206
	v_add_f32_e32 v66, v66, v126
	v_exp_f32_e32 v207, v207
	v_add_f32_e32 v67, v67, v127
	v_cvt_pk_bf16_f32 v208, v112, v113
	v_cvt_pk_bf16_f32 v209, v114, v115
	v_cvt_pk_bf16_f32 v210, v116, v117
	v_cvt_pk_bf16_f32 v211, v118, v119
	v_cvt_pk_bf16_f32 v212, v120, v121
	v_cvt_pk_bf16_f32 v213, v122, v123
	v_cvt_pk_bf16_f32 v214, v124, v125
	v_cvt_pk_bf16_f32 v215, v126, v127
	v_add_f32_e32 v64, v64, v192
	v_add_f32_e32 v65, v65, v193
	v_add_f32_e32 v66, v66, v194
	v_add_f32_e32 v67, v67, v195
	v_add_f32_e32 v64, v64, v196
	v_add_f32_e32 v65, v65, v197
	v_add_f32_e32 v66, v66, v198
	v_add_f32_e32 v67, v67, v199
	v_add_f32_e32 v64, v64, v200
	v_add_f32_e32 v65, v65, v201
	v_add_f32_e32 v66, v66, v202
	v_add_f32_e32 v67, v67, v203
	v_add_f32_e32 v64, v64, v204
	v_add_f32_e32 v65, v65, v205
	v_add_f32_e32 v66, v66, v206
	v_add_f32_e32 v67, v67, v207
	v_cvt_pk_bf16_f32 v216, v192, v193
	v_cvt_pk_bf16_f32 v217, v194, v195
	v_cvt_pk_bf16_f32 v218, v196, v197
	v_cvt_pk_bf16_f32 v219, v198, v199
	v_cvt_pk_bf16_f32 v220, v200, v201
	v_cvt_pk_bf16_f32 v221, v202, v203
	v_cvt_pk_bf16_f32 v222, v204, v205
	v_cvt_pk_bf16_f32 v223, v206, v207
	s_nop 1
	s_waitcnt vmcnt(0)
	s_barrier
	s_setprio 1
	ds_read_b64_tr_b16 v[84:85], v168 offset:0
	ds_read_b64_tr_b16 v[86:87], v168 offset:2048
	ds_read_b64_tr_b16 v[88:89], v168 offset:4096
	ds_read_b64_tr_b16 v[90:91], v168 offset:6144
	ds_read_b64_tr_b16 v[92:93], v168 offset:8192
	ds_read_b64_tr_b16 v[94:95], v168 offset:10240
	ds_read_b64_tr_b16 v[128:129], v168 offset:12288
	ds_read_b64_tr_b16 v[130:131], v168 offset:14336
	ds_read_b64_tr_b16 v[132:133], v168 offset:512
	ds_read_b64_tr_b16 v[134:135], v168 offset:2560
	ds_read_b64_tr_b16 v[140:141], v168 offset:4608
	ds_read_b64_tr_b16 v[142:143], v168 offset:6656
	ds_read_b64_tr_b16 v[152:153], v168 offset:8704
	ds_read_b64_tr_b16 v[154:155], v168 offset:10752
	s_waitcnt lgkmcnt(12)
	v_mfma_f32_32x32x16_bf16 v[0:15], v[208:211], v[84:87], v[0:15]
	ds_read_b64_tr_b16 v[160:161], v168 offset:12800
	ds_read_b64_tr_b16 v[162:163], v168 offset:14848
	s_waitcnt lgkmcnt(12)
	v_mfma_f32_32x32x16_bf16 v[0:15], v[212:215], v[88:91], v[0:15]
	ds_read_b64_tr_b16 v[84:85], v168 offset:1024
	ds_read_b64_tr_b16 v[86:87], v168 offset:3072
	s_waitcnt lgkmcnt(12)
	v_mfma_f32_32x32x16_bf16 v[0:15], v[216:219], v[92:95], v[0:15]
	ds_read_b64_tr_b16 v[88:89], v168 offset:5120
	ds_read_b64_tr_b16 v[90:91], v168 offset:7168
	s_waitcnt lgkmcnt(12)
	v_mfma_f32_32x32x16_bf16 v[0:15], v[220:223], v[128:131], v[0:15]
	ds_read_b64_tr_b16 v[92:93], v168 offset:9216
	ds_read_b64_tr_b16 v[94:95], v168 offset:11264
	s_waitcnt lgkmcnt(12)
	v_mfma_f32_32x32x16_bf16 v[16:31], v[208:211], v[132:135], v[16:31]
	ds_read_b64_tr_b16 v[128:129], v168 offset:13312
	ds_read_b64_tr_b16 v[130:131], v168 offset:15360
	s_waitcnt lgkmcnt(12)
	v_mfma_f32_32x32x16_bf16 v[16:31], v[212:215], v[140:143], v[16:31]
	ds_read_b64_tr_b16 v[132:133], v168 offset:1536
	ds_read_b64_tr_b16 v[134:135], v168 offset:3584
	s_waitcnt lgkmcnt(12)
	v_mfma_f32_32x32x16_bf16 v[16:31], v[216:219], v[152:155], v[16:31]
	ds_read_b64_tr_b16 v[140:141], v168 offset:5632
	ds_read_b64_tr_b16 v[142:143], v168 offset:7680
	s_waitcnt lgkmcnt(12)
	v_mfma_f32_32x32x16_bf16 v[16:31], v[220:223], v[160:163], v[16:31]
	ds_read_b64_tr_b16 v[152:153], v168 offset:9728
	ds_read_b64_tr_b16 v[154:155], v168 offset:11776
	s_waitcnt lgkmcnt(12)
	v_mfma_f32_32x32x16_bf16 v[32:47], v[208:211], v[84:87], v[32:47]
	ds_read_b64_tr_b16 v[160:161], v168 offset:13824
	ds_read_b64_tr_b16 v[162:163], v168 offset:15872
	v_xor_b32_e32 v168, 0x4000, v168
	s_waitcnt lgkmcnt(12)
	v_mfma_f32_32x32x16_bf16 v[32:47], v[212:215], v[88:91], v[32:47]
	s_waitcnt lgkmcnt(10)
	v_mfma_f32_32x32x16_bf16 v[32:47], v[216:219], v[92:95], v[32:47]
	s_waitcnt lgkmcnt(8)
	v_mfma_f32_32x32x16_bf16 v[32:47], v[220:223], v[128:131], v[32:47]
	s_waitcnt lgkmcnt(6)
	v_mfma_f32_32x32x16_bf16 v[48:63], v[208:211], v[132:135], v[48:63]
	s_waitcnt lgkmcnt(4)
	v_mfma_f32_32x32x16_bf16 v[48:63], v[212:215], v[140:143], v[48:63]
	s_waitcnt lgkmcnt(2)
	v_mfma_f32_32x32x16_bf16 v[48:63], v[216:219], v[152:155], v[48:63]
	s_waitcnt lgkmcnt(0)
	v_mfma_f32_32x32x16_bf16 v[48:63], v[220:223], v[160:163], v[48:63]
	s_barrier
	s_barrier
	s_branch .Lat_done
.Lat_g1:
	s_barrier
	s_setprio 1
	ds_read_b128 v[224:227], v164
	ds_read_b128 v[228:231], v164 offset:8192
	ds_read_b128 v[232:235], v165
	ds_read_b128 v[236:239], v165 offset:8192
	ds_read_b128 v[240:243], v166
	ds_read_b128 v[244:247], v166 offset:8192
	ds_read_b128 v[248:251], v167
	ds_read_b128 v[188:191], v167 offset:8192
	v_add_u32_e32 v164, s100, v164
	v_add_u32_e32 v165, s100, v165
	v_add_u32_e32 v166, s100, v166
	v_add_u32_e32 v167, s100, v167
	s_waitcnt lgkmcnt(7)
	v_mfma_f32_32x32x16_bf16 v[112:127], v[224:227], v[108:111], v[68:83]
	s_waitcnt lgkmcnt(6)
	v_mfma_f32_32x32x16_bf16 v[192:207], v[228:231], v[108:111], v[68:83]
	s_waitcnt lgkmcnt(5)
	v_mfma_f32_32x32x16_bf16 v[112:127], v[232:235], v[104:107], v[112:127]
	s_waitcnt lgkmcnt(4)
	v_mfma_f32_32x32x16_bf16 v[192:207], v[236:239], v[104:107], v[192:207]
	s_waitcnt lgkmcnt(3)
	v_mfma_f32_32x32x16_bf16 v[112:127], v[240:243], v[100:103], v[112:127]
	s_waitcnt lgkmcnt(2)
	v_mfma_f32_32x32x16_bf16 v[192:207], v[244:247], v[100:103], v[192:207]
	s_waitcnt lgkmcnt(1)
	v_mfma_f32_32x32x16_bf16 v[112:127], v[248:251], v[96:99], v[112:127]
	s_waitcnt lgkmcnt(0)
	v_mfma_f32_32x32x16_bf16 v[192:207], v[188:191], v[96:99], v[192:207]
	s_nop 7
	s_nop 3
	s_barrier

; #define SBAR() __builtin_amdgcn_sched_barrier(0)
; __device__ __forceinline__ void qkt(f32x16& p0, f32x16& p1, const char* Ks, const bf16x8* qr, float c0, int r32, int hi, int half) {
;     ...
;     bf16x8 a0 = KFRAG(0, r32), a1 = KFRAG(0, 32 + r32), b0 = KFRAG(1, r32), b1 = KFRAG(1, 32 + r32);
;     SBAR();
; #pragma unroll
;     for (int r = 0; r < 16; ++r) { p0[r] = c0; p1[r] = c0; }
;     SBAR();
;     p0 = __builtin_amdgcn_mfma_f32_32x32x16_bf16(a0, qr[0], p0, 0, 0, 0); p1 = __builtin_amdgcn_mfma_f32_32x32x16_bf16(a1, qr[0], p1, 0, 0, 0);
;     a0 = KFRAG(2, r32); a1 = KFRAG(2, 32 + r32);
;     SBAR();
;     p0 = __builtin_amdgcn_mfma_f32_32x32x16_bf16(b0, qr[1], p0, 0, 0, 0); p1 = __builtin_amdgcn_mfma_f32_32x32x16_bf16(b1, qr[1], p1, 0, 0, 0);
;     b0 = KFRAG(3, r32); b1 = KFRAG(3, 32 + r32);
;     SBAR();
;     p0 = __builtin_amdgcn_mfma_f32_32x32x16_bf16(a0, qr[2], p0, 0, 0, 0); p1 = __builtin_amdgcn_mfma_f32_32x32x16_bf16(a1, qr[2], p1, 0, 0, 0);
;     p0 = __builtin_amdgcn_mfma_f32_32x32x16_bf16(b0, qr[3], p0, 0, 0, 0); p1 = __builtin_amdgcn_mfma_f32_32x32x16_bf16(b1, qr[3], p1, 0, 0, 0);
;     ...
; }
; __device__ __forceinline__ int v_st(int k, int c) { const int kk = (k & ~0xC) | ((k & 4) << 1) | ((k & 8) >> 1); return ((kk >> 3) * 4 + (c >> 5)) * 512 + ((kk & 7) * 32 + (c & 31)) * 2; }
; __device__ __forceinline__ int v_rd_base(int lane) { return ((lane & 3) << 3) | (((lane >> 2) & 3) << 6) | (((lane >> 4) & 1) << 5) | (((lane >> 5) & 1) << 8); }
; template <int OFF> __device__ __forceinline__ s16x4 tr_read(int vb) { s16x4 r; asm volatile("ds_read_b64_tr_b16 %0, %1 offset:%2" : "=&v"(r) : "v"(vb), "i"(OFF) : "memory"); return r; }
; template <int MODE>
; __device__ __forceinline__ void attn_unit(const UnitArgs& A, char* lds, const int wave_) {
;     ...
;     for (int j = 1; j + 1 < NT; j += 2) {
;         SBAR(); QK(pB0, pB1, K_lds + SHM_K, j);
;         finishSM(pA0, pA1, l_reg, pa0, pa1, pa2, pa3); SBAR();
;         SLOAD(0, j + 1); SBAR();
;         post(pB0, pB1, j); PV(0, pB0, pB1);
;         __syncthreads(); SWAIT(); SWRITE(0, 0);
;         __syncthreads();
;         SBAR(); QK(pA0, pA1, K_lds, j + 1);
;         finishSM(pB0, pB1, l_reg, pa0, pa1, pa2, pa3); SBAR();
;         SLOAD(0, j + 2); SBAR();
;         post(pA0, pA1, j + 1); PV(1, pA0, pA1);
;         __syncthreads(); SWAIT(); SWRITE(1, 0);
;         __syncthreads();
.Lat_c0same_g1l:
	ds_read_b128 v[224:227], v164
	ds_read_b128 v[228:231], v164 offset:8192
	ds_read_b128 v[232:235], v165
	ds_read_b128 v[236:239], v165 offset:8192
	ds_read_b128 v[240:243], v166
	ds_read_b128 v[244:247], v166 offset:8192
	ds_read_b128 v[248:251], v167
	ds_read_b128 v[188:191], v167 offset:8192
	v_add_u32_e32 v164, s101, v164
	v_add_u32_e32 v165, s101, v165
	v_add_u32_e32 v166, s101, v166
	v_add_u32_e32 v167, s101, v167
	s_waitcnt vmcnt(4)
	s_barrier
	s_setprio 1
	s_waitcnt lgkmcnt(7)
	v_mfma_f32_32x32x16_bf16 v[112:127], v[224:227], v[108:111], v[68:83]
	s_waitcnt lgkmcnt(6)
	v_mfma_f32_32x32x16_bf16 v[192:207], v[228:231], v[108:111], v[68:83]
	ds_read_b64_tr_b16 v[84:85], v168 offset:0
	ds_read_b64_tr_b16 v[86:87], v168 offset:2048
	s_waitcnt lgkmcnt(7)
	v_mfma_f32_32x32x16_bf16 v[112:127], v[232:235], v[104:107], v[112:127]
	ds_read_b64_tr_b16 v[88:89], v168 offset:4096
	ds_read_b64_tr_b16 v[90:91], v168 offset:6144
	s_waitcnt lgkmcnt(8)
	v_mfma_f32_32x32x16_bf16 v[192:207], v[236:239], v[104:107], v[192:207]
	ds_read_b64_tr_b16 v[92:93], v168 offset:8192
	ds_read_b64_tr_b16 v[94:95], v168 offset:10240
	s_waitcnt lgkmcnt(9)
	v_mfma_f32_32x32x16_bf16 v[112:127], v[240:243], v[100:103], v[112:127]
	ds_read_b64_tr_b16 v[128:129], v168 offset:12288
	ds_read_b64_tr_b16 v[130:131], v168 offset:14336
	s_waitcnt lgkmcnt(10)
	v_mfma_f32_32x32x16_bf16 v[192:207], v[244:247], v[100:103], v[192:207]
	ds_read_b64_tr_b16 v[132:133], v168 offset:512
	ds_read_b64_tr_b16 v[134:135], v168 offset:2560
	s_waitcnt lgkmcnt(11)
	v_mfma_f32_32x32x16_bf16 v[112:127], v[248:251], v[96:99], v[112:127]
	ds_read_b64_tr_b16 v[140:141], v168 offset:4608
	ds_read_b64_tr_b16 v[142:143], v168 offset:6656
	s_waitcnt lgkmcnt(12)
	v_mfma_f32_32x32x16_bf16 v[192:207], v[188:191], v[96:99], v[192:207]
	ds_read_b64_tr_b16 v[152:153], v168 offset:8704
	ds_read_b64_tr_b16 v[154:155], v168 offset:10752
	s_waitcnt lgkmcnt(12)
	v_mfma_f32_32x32x16_bf16 v[0:15], v[208:211], v[84:87], v[0:15]
	ds_read_b64_tr_b16 v[160:161], v168 offset:12800
	ds_read_b64_tr_b16 v[162:163], v168 offset:14848
	s_waitcnt lgkmcnt(12)
	v_mfma_f32_32x32x16_bf16 v[0:15], v[212:215], v[88:91], v[0:15]
	ds_read_b64_tr_b16 v[84:85], v168 offset:1024
	ds_read_b64_tr_b16 v[86:87], v168 offset:3072
	s_waitcnt lgkmcnt(12)
	v_mfma_f32_32x32x16_bf16 v[0:15], v[216:219], v[92:95], v[0:15]
	ds_read_b64_tr_b16 v[88:89], v168 offset:5120
	ds_read_b64_tr_b16 v[90:91], v168 offset:7168
	s_waitcnt lgkmcnt(12)
	v_mfma_f32_32x32x16_bf16 v[0:15], v[220:223], v[128:131], v[0:15]
	ds_read_b64_tr_b16 v[92:93], v168 offset:9216
	ds_read_b64_tr_b16 v[94:95], v168 offset:11264
	s_waitcnt lgkmcnt(12)
	v_mfma_f32_32x32x16_bf16 v[16:31], v[208:211], v[132:135], v[16:31]
	ds_read_b64_tr_b16 v[128:129], v168 offset:13312
	ds_read_b64_tr_b16 v[130:131], v168 offset:15360
	s_waitcnt lgkmcnt(12)
	v_mfma_f32_32x32x16_bf16 v[16:31], v[212:215], v[140:143], v[16:31]
	ds_read_b64_tr_b16 v[132:133], v168 offset:1536
	ds_read_b64_tr_b16 v[134:135], v168 offset:3584
	s_waitcnt lgkmcnt(12)
	v_mfma_f32_32x32x16_bf16 v[16:31], v[216:219], v[152:155], v[16:31]
	ds_read_b64_tr_b16 v[140:141], v168 offset:5632
	ds_read_b64_tr_b16 v[142:143], v168 offset:7680
	s_waitcnt lgkmcnt(12)
	v_mfma_f32_32x32x16_bf16 v[16:31], v[220:223], v[160:163], v[16:31]
	ds_read_b64_tr_b16 v[152:153], v168 offset:9728
	ds_read_b64_tr_b16 v[154:155], v168 offset:11776
	s_waitcnt lgkmcnt(12)
	v_mfma_f32_32x32x16_bf16 v[32:47], v[208:211], v[84:87], v[32:47]
	ds_read_b64_tr_b16 v[160:161], v168 offset:13824
	ds_read_b64_tr_b16 v[162:163], v168 offset:15872
	v_xor_b32_e32 v168, 0x4000, v168
	s_waitcnt lgkmcnt(12)
	v_mfma_f32_32x32x16_bf16 v[32:47], v[212:215], v[88:91], v[32:47]
	s_waitcnt lgkmcnt(10)
	v_mfma_f32_32x32x16_bf16 v[32:47], v[216:219], v[92:95], v[32:47]
	s_waitcnt lgkmcnt(8)
	v_mfma_f32_32x32x16_bf16 v[32:47], v[220:223], v[128:131], v[32:47]
	s_waitcnt lgkmcnt(6)
	v_mfma_f32_32x32x16_bf16 v[48:63], v[208:211], v[132:135], v[48:63]
	s_waitcnt lgkmcnt(4)
	v_mfma_f32_32x32x16_bf16 v[48:63], v[212:215], v[140:143], v[48:63]
	s_waitcnt lgkmcnt(2)
	v_mfma_f32_32x32x16_bf16 v[48:63], v[216:219], v[152:155], v[48:63]
	s_waitcnt lgkmcnt(0)
	v_mfma_f32_32x32x16_bf16 v[48:63], v[220:223], v[160:163], v[48:63]
	s_add_i32 s34, s34, 1
	s_add_i32 s23, s23, 64
	s_addk_i32 s35, 0x100
	s_mov_b32 s8, s100
	s_mov_b32 s100, s101
	s_mov_b32 s101, s32
	s_mov_b32 s32, s8
	s_waitcnt vmcnt(2)
	s_barrier
	s_cmp_lt_u32 s34, s20
	s_cbranch_scc1 .Lat_g1_loop
	s_setprio 0
	s_cmp_gt_i32 s23, s29
	s_cselect_b32 s99, 1, 0
	s_cmp_lt_i32 s23, s30
	s_cselect_b32 s6, 1, 0
	s_and_b32 s99, s99, s6
	s_cbranch_scc0 .Lat_far_g1p
	v_add_u32_e32 v186, s35, v174
	ds_read2_b32 v[224:225], v186 offset0:0 offset1:1
	ds_read2_b32 v[226:227], v186 offset0:2 offset1:3
	ds_read2_b32 v[228:229], v186 offset0:8 offset1:9
	ds_read2_b32 v[230:231], v186 offset0:10 offset1:11
	ds_read2_b32 v[232:233], v186 offset0:16 offset1:17
	ds_read2_b32 v[234:235], v186 offset0:18 offset1:19
	ds_read2_b32 v[236:237], v186 offset0:24 offset1:25
	ds_read2_b32 v[238:239], v186 offset0:26 offset1:27
	s_waitcnt lgkmcnt(4)
	ds_read2_b32 v[240:241], v186 offset0:32 offset1:33
	ds_read2_b32 v[242:243], v186 offset0:34 offset1:35
	ds_read2_b32 v[244:245], v186 offset0:40 offset1:41
	ds_read2_b32 v[246:247], v186 offset0:42 offset1:43
	ds_read2_b32 v[248:249], v186 offset0:48 offset1:49
	ds_read2_b32 v[250:251], v186 offset0:50 offset1:51
	ds_read2_b32 v[188:189], v186 offset0:56 offset1:57
	ds_read2_b32 v[190:191], v186 offset0:58 offset1:59
	s_waitcnt lgkmcnt(8)
	v_add_f32_e32 v112, v112, v224
	v_add_f32_e32 v113, v113, v225
	v_add_f32_e32 v114, v114, v226
	v_add_f32_e32 v115, v115, v227
	v_add_f32_e32 v116, v116, v228
	v_add_f32_e32 v117, v117, v229
	v_add_f32_e32 v118, v118, v230
	v_add_f32_e32 v119, v119, v231
	v_add_f32_e32 v120, v120, v232
	v_add_f32_e32 v121, v121, v233
	v_add_f32_e32 v122, v122, v234
	v_add_f32_e32 v123, v123, v235
	v_add_f32_e32 v124, v124, v236
	v_add_f32_e32 v125, v125, v237
	v_add_f32_e32 v126, v126, v238
	v_add_f32_e32 v127, v127, v239
	s_waitcnt lgkmcnt(0)
	v_add_f32_e32 v192, v192, v240
	v_add_f32_e32 v193, v193, v241
	v_add_f32_e32 v194, v194, v242
	v_add_f32_e32 v195, v195, v243
	v_add_f32_e32 v196, v196, v244
	v_add_f32_e32 v197, v197, v245
	v_add_f32_e32 v198, v198, v246
	v_add_f32_e32 v199, v199, v247
	v_add_f32_e32 v200, v200, v248
	v_add_f32_e32 v201, v201, v249
	v_add_f32_e32 v202, v202, v250
	v_add_f32_e32 v203, v203, v251
	v_add_f32_e32 v204, v204, v188
	v_add_f32_e32 v205, v205, v189
	v_add_f32_e32 v206, v206, v190
	v_add_f32_e32 v207, v207, v191
; #define SBAR() __builtin_amdgcn_sched_barrier(0)
; #define PVLOAD(D0, X) do { X[0] = tr_read<v_rd_off(D0, 0, 0)>(vb); X[1] = tr_read<v_rd_off(D0, 0, 1)>(vb); X[2] = tr_read<v_rd_off(D0, 1, 0)>(vb); X[3] = tr_read<v_rd_off(D0, 1, 1)>(vb); \
;     X[4] = tr_read<v_rd_off(D0, 2, 0)>(vb); X[5] = tr_read<v_rd_off(D0, 2, 1)>(vb); X[6] = tr_read<v_rd_off(D0, 3, 0)>(vb); X[7] = tr_read<v_rd_off(D0, 3, 1)>(vb); } while (0)
; #define PVMMA(OD, X) do { OD = __builtin_amdgcn_mfma_f32_32x32x16_bf16(pa0, PVPK(X[0], X[1]), OD, 0, 0, 0); OD = __builtin_amdgcn_mfma_f32_32x32x16_bf16(pa1, PVPK(X[2], X[3]), OD, 0, 0, 0); \
;     OD = __builtin_amdgcn_mfma_f32_32x32x16_bf16(pa2, PVPK(X[4], X[5]), OD, 0, 0, 0); OD = __builtin_amdgcn_mfma_f32_32x32x16_bf16(pa3, PVPK(X[6], X[7]), OD, 0, 0, 0); } while (0)
; #define PVWAIT() do { asm volatile("s_waitcnt lgkmcnt(0)" ::: "memory"); SBAR(); } while (0)
; #define PVEXP(P, B, N) do { _Pragma("unroll") for (int r = (B); r < (B) + (N); ++r) P[r] = __builtin_amdgcn_exp2f(P[r]); } while (0)
; __device__ __forceinline__ void expHalf(f32x16& p0) {
; #pragma unroll
;     for (int r = 0; r < 16; ++r) p0[r] = __builtin_amdgcn_exp2f(p0[r]);
; }
; __device__ __forceinline__ void finishSM(f32x16& p0, f32x16& p1, float& l_reg, bf16x8& pa0, bf16x8& pa1, bf16x8& pa2, bf16x8& pa3) {
;     float ps = 0;
; #pragma unroll
;     for (int r = 0; r < 16; ++r) ps += p0[r];
; #pragma unroll
;     for (int r = 0; r < 16; ++r) ps += p1[r];
;     l_reg += ps;
;     ...
;     PK4(p0, 0, pa0); PK4(p0, 8, pa1); PK4(p1, 0, pa2); PK4(p1, 8, pa3);
;     ...
; }
; template <int NB> __device__ __forceinline__ void pv_blocks(f32x16* o, int vb, bf16x8 pa0, bf16x8 pa1, bf16x8 pa2, bf16x8 pa3, f32x16& pe0, f32x16& pe1) {
;     s16x4 x[8], y[8];
;     ...
;     PVLOAD(0, x); PVWAIT();
;     if (NB == 4) {
;         PVLOAD(1, y); SBAR(); PVMMA(o[0], x); PVEXP(pe0, 0, 8); SBAR(); PVWAIT();
;         PVLOAD(2, x); SBAR(); PVMMA(o[1], y); PVEXP(pe0, 8, 8); SBAR(); PVWAIT();
;         PVLOAD(3, y); SBAR(); PVMMA(o[2], x); PVEXP(pe1, 0, 8); SBAR(); PVWAIT();
;         PVMMA(o[3], y); PVEXP(pe1, 8, 8);
;     } else {
;         PVLOAD(1, y); SBAR(); PVMMA(o[0], x); PVEXP(pe0, 0, 16); SBAR(); PVWAIT();
;         PVMMA(o[1], y); PVEXP(pe1, 0, 16);
;     }
;     ...
; }
.Lat_far_g1p:
	v_exp_f32_e32 v112, v112
	v_exp_f32_e32 v113, v113
	v_exp_f32_e32 v114, v114
	v_exp_f32_e32 v115, v115
	v_exp_f32_e32 v116, v116
	v_exp_f32_e32 v117, v117
	v_exp_f32_e32 v118, v118
	v_exp_f32_e32 v119, v119
	v_exp_f32_e32 v120, v120
	v_exp_f32_e32 v121, v121
	v_exp_f32_e32 v122, v122
	v_exp_f32_e32 v123, v123
	v_exp_f32_e32 v124, v124
	v_exp_f32_e32 v125, v125
	v_exp_f32_e32 v126, v126
	v_exp_f32_e32 v127, v127
	v_exp_f32_e32 v192, v192
	v_add_f32_e32 v64, v64, v112
	v_exp_f32_e32 v193, v193
	v_add_f32_e32 v65, v65, v113
	v_exp_f32_e32 v194, v194
	v_add_f32_e32 v66, v66, v114
	v_exp_f32_e32 v195, v195
	v_add_f32_e32 v67, v67, v115
	v_exp_f32_e32 v196, v196
	v_add_f32_e32 v64, v64, v116
	v_exp_f32_e32 v197, v197
	v_add_f32_e32 v65, v65, v117
	v_exp_f32_e32 v198, v198
	v_add_f32_e32 v66, v66, v118
	v_exp_f32_e32 v199, v199
	v_add_f32_e32 v67, v67, v119
	v_exp_f32_e32 v200, v200
	v_add_f32_e32 v64, v64, v120
	v_exp_f32_e32 v201, v201
	v_add_f32_e32 v65, v65, v121
	v_exp_f32_e32 v202, v202
	v_add_f32_e32 v66, v66, v122
	v_exp_f32_e32 v203, v203
	v_add_f32_e32 v67, v67, v123
	v_exp_f32_e32 v204, v204
	v_add_f32_e32 v64, v64, v124
	v_exp_f32_e32 v205, v205
	v_add_f32_e32 v65, v65, v125
	v_exp_f32_e32 v206, v206
	v_add_f32_e32 v66, v66, v126
	v_exp_f32_e32 v207, v207
	v_add_f32_e32 v67, v67, v127
	v_cvt_pk_bf16_f32 v208, v112, v113
	v_cvt_pk_bf16_f32 v209, v114, v115
	v_cvt_pk_bf16_f32 v210, v116, v117
	v_cvt_pk_bf16_f32 v211, v118, v119
	v_cvt_pk_bf16_f32 v212, v120, v121
	v_cvt_pk_bf16_f32 v213, v122, v123
	v_cvt_pk_bf16_f32 v214, v124, v125
	v_cvt_pk_bf16_f32 v215, v126, v127
	v_add_f32_e32 v64, v64, v192
	v_add_f32_e32 v65, v65, v193
	v_add_f32_e32 v66, v66, v194
	v_add_f32_e32 v67, v67, v195
	v_add_f32_e32 v64, v64, v196
	v_add_f32_e32 v65, v65, v197
	v_add_f32_e32 v66, v66, v198
	v_add_f32_e32 v67, v67, v199
	v_add_f32_e32 v64, v64, v200
	v_add_f32_e32 v65, v65, v201
	v_add_f32_e32 v66, v66, v202
	v_add_f32_e32 v67, v67, v203
	v_add_f32_e32 v64, v64, v204
	v_add_f32_e32 v65, v65, v205
	v_add_f32_e32 v66, v66, v206
	v_add_f32_e32 v67, v67, v207
	v_cvt_pk_bf16_f32 v216, v192, v193
	v_cvt_pk_bf16_f32 v217, v194, v195
	v_cvt_pk_bf16_f32 v218, v196, v197
	v_cvt_pk_bf16_f32 v219, v198, v199
	v_cvt_pk_bf16_f32 v220, v200, v201
	v_cvt_pk_bf16_f32 v221, v202, v203
	v_cvt_pk_bf16_f32 v222, v204, v205
	v_cvt_pk_bf16_f32 v223, v206, v207
	s_nop 1
	s_waitcnt vmcnt(0)
	s_barrier
	s_setprio 1
	ds_read_b64_tr_b16 v[84:85], v168 offset:0
	ds_read_b64_tr_b16 v[86:87], v168 offset:2048
	ds_read_b64_tr_b16 v[88:89], v168 offset:4096
	ds_read_b64_tr_b16 v[90:91], v168 offset:6144
	ds_read_b64_tr_b16 v[92:93], v168 offset:8192
	ds_read_b64_tr_b16 v[94:95], v168 offset:10240
	ds_read_b64_tr_b16 v[128:129], v168 offset:12288
	ds_read_b64_tr_b16 v[130:131], v168 offset:14336
	ds_read_b64_tr_b16 v[132:133], v168 offset:512
	ds_read_b64_tr_b16 v[134:135], v168 offset:2560
	ds_read_b64_tr_b16 v[140:141], v168 offset:4608
	ds_read_b64_tr_b16 v[142:143], v168 offset:6656
	ds_read_b64_tr_b16 v[152:153], v168 offset:8704
	ds_read_b64_tr_b16 v[154:155], v168 offset:10752
	s_waitcnt lgkmcnt(12)
	v_mfma_f32_32x32x16_bf16 v[0:15], v[208:211], v[84:87], v[0:15]
	ds_read_b64_tr_b16 v[160:161], v168 offset:12800
	ds_read_b64_tr_b16 v[162:163], v168 offset:14848
	s_waitcnt lgkmcnt(12)
	v_mfma_f32_32x32x16_bf16 v[0:15], v[212:215], v[88:91], v[0:15]
	ds_read_b64_tr_b16 v[84:85], v168 offset:1024
	ds_read_b64_tr_b16 v[86:87], v168 offset:3072
	s_waitcnt lgkmcnt(12)
	v_mfma_f32_32x32x16_bf16 v[0:15], v[216:219], v[92:95], v[0:15]
	ds_read_b64_tr_b16 v[88:89], v168 offset:5120
	ds_read_b64_tr_b16 v[90:91], v168 offset:7168
	s_waitcnt lgkmcnt(12)
	v_mfma_f32_32x32x16_bf16 v[0:15], v[220:223], v[128:131], v[0:15]
	ds_read_b64_tr_b16 v[92:93], v168 offset:9216
	ds_read_b64_tr_b16 v[94:95], v168 offset:11264
	s_waitcnt lgkmcnt(12)
	v_mfma_f32_32x32x16_bf16 v[16:31], v[208:211], v[132:135], v[16:31]
	ds_read_b64_tr_b16 v[128:129], v168 offset:13312
	ds_read_b64_tr_b16 v[130:131], v168 offset:15360
	s_waitcnt lgkmcnt(12)
	v_mfma_f32_32x32x16_bf16 v[16:31], v[212:215], v[140:143], v[16:31]
	ds_read_b64_tr_b16 v[132:133], v168 offset:1536
	ds_read_b64_tr_b16 v[134:135], v168 offset:3584
	s_waitcnt lgkmcnt(12)
	v_mfma_f32_32x32x16_bf16 v[16:31], v[216:219], v[152:155], v[16:31]
	ds_read_b64_tr_b16 v[140:141], v168 offset:5632
	ds_read_b64_tr_b16 v[142:143], v168 offset:7680
	s_waitcnt lgkmcnt(12)
	v_mfma_f32_32x32x16_bf16 v[16:31], v[220:223], v[160:163], v[16:31]
	ds_read_b64_tr_b16 v[152:153], v168 offset:9728
	ds_read_b64_tr_b16 v[154:155], v168 offset:11776
	s_waitcnt lgkmcnt(12)
	v_mfma_f32_32x32x16_bf16 v[32:47], v[208:211], v[84:87], v[32:47]
	ds_read_b64_tr_b16 v[160:161], v168 offset:13824
	ds_read_b64_tr_b16 v[162:163], v168 offset:15872
	v_xor_b32_e32 v168, 0x4000, v168
	s_waitcnt lgkmcnt(12)
	v_mfma_f32_32x32x16_bf16 v[32:47], v[212:215], v[88:91], v[32:47]
	s_waitcnt lgkmcnt(10)
	v_mfma_f32_32x32x16_bf16 v[32:47], v[216:219], v[92:95], v[32:47]
	s_waitcnt lgkmcnt(8)
	v_mfma_f32_32x32x16_bf16 v[32:47], v[220:223], v[128:131], v[32:47]
	s_waitcnt lgkmcnt(6)
	v_mfma_f32_32x32x16_bf16 v[48:63], v[208:211], v[132:135], v[48:63]
	s_waitcnt lgkmcnt(4)
	v_mfma_f32_32x32x16_bf16 v[48:63], v[212:215], v[140:143], v[48:63]
	s_waitcnt lgkmcnt(2)
	v_mfma_f32_32x32x16_bf16 v[48:63], v[216:219], v[152:155], v[48:63]
	s_waitcnt lgkmcnt(0)
	v_mfma_f32_32x32x16_bf16 v[48:63], v[220:223], v[160:163], v[48:63]
	s_waitcnt vmcnt(0)
	s_barrier
